# gate epilogues of the co/ho GEMMs de-serialised: tile loads issued in batches up front (one wait per batch) instead of a load-wait-store ladder
# baseline (speedup 1.0000x reference)
.LBB0_763:
	v_mov_b32_e32 v130, v136
	s_lshl_b32 s2, s2, 8
	s_add_i32 s2, s2, s70
	v_and_or_b32 v132, v130, 15, s2
	s_lshl_b32 s2, s3, 8
	v_lshrrev_b32_e32 v130, 1, v130
	v_and_or_b32 v130, v130, 24, s2
	v_or_b32_e32 v130, s71, v130
	v_ashrrev_i32_e32 v133, 31, v132
	v_ashrrev_i32_e32 v131, 31, v130
	v_lshlrev_b64 v[134:135], 11, v[132:133]
	v_lshl_add_u64 v[140:141], s[24:25], 0, v[134:135]
	v_lshlrev_b64 v[134:135], 1, v[130:131]
	v_lshl_add_u64 v[130:131], v[140:141], 0, v[134:135]
	global_load_dwordx4 v[146:149], v[130:131], off
	global_load_dwordx4 v[150:153], v[130:131], off offset:256
	s_mov_b64 s[98:99], 0x8000
	v_lshl_add_u64 v[240:241], v[130:131], 0, s[98:99]
	global_load_dwordx4 v[154:157], v[240:241], off
	global_load_dwordx4 v[158:161], v[240:241], off offset:256
	s_mov_b64 s[98:99], 0x10000
	v_lshl_add_u64 v[240:241], v[130:131], 0, s[98:99]
	global_load_dwordx4 v[162:165], v[240:241], off
	global_load_dwordx4 v[182:185], v[240:241], off offset:256
	s_mov_b64 s[98:99], 0x18000
	v_lshl_add_u64 v[240:241], v[130:131], 0, s[98:99]
	global_load_dwordx4 v[186:189], v[240:241], off
	global_load_dwordx4 v[190:193], v[240:241], off offset:256
	s_mov_b64 s[98:99], 0x40000
	v_lshl_add_u64 v[240:241], v[130:131], 0, s[98:99]
	global_load_dwordx4 v[194:197], v[240:241], off
	global_load_dwordx4 v[198:201], v[240:241], off offset:256
	s_mov_b64 s[98:99], 0x48000
	v_lshl_add_u64 v[240:241], v[130:131], 0, s[98:99]
	global_load_dwordx4 v[202:205], v[240:241], off
	global_load_dwordx4 v[206:209], v[240:241], off offset:256
	s_mov_b64 s[98:99], 0x50000
	v_lshl_add_u64 v[240:241], v[130:131], 0, s[98:99]
	global_load_dwordx4 v[220:223], v[240:241], off
	global_load_dwordx4 v[224:227], v[240:241], off offset:256
	s_mov_b64 s[98:99], 0x58000
	v_lshl_add_u64 v[240:241], v[130:131], 0, s[98:99]
	global_load_dwordx4 v[228:231], v[240:241], off
	global_load_dwordx4 v[232:235], v[240:241], off offset:256
	s_waitcnt vmcnt(0)
	s_mov_b64 s[2:3], 0x48000
	v_lshlrev_b32_e32 v144, 16, v146
	v_and_b32_e32 v145, 0xffff0000, v146
	v_lshlrev_b32_e32 v140, 16, v147
	v_and_b32_e32 v141, 0xffff0000, v147
	v_pk_mul_f32 v[126:127], v[126:127], v[140:141]
	v_lshlrev_b32_e32 v140, 16, v148
	v_and_b32_e32 v141, 0xffff0000, v148
	v_pk_mul_f32 v[140:141], v[120:121], v[140:141]
	v_lshlrev_b32_e32 v120, 16, v149
	v_and_b32_e32 v121, 0xffff0000, v149
	v_pk_mul_f32 v[124:125], v[124:125], v[144:145]
	v_pk_mul_f32 v[142:143], v[122:123], v[120:121]
	v_cvt_pk_bf16_f32 v120, v124, v125
	v_cvt_pk_bf16_f32 v121, v126, v127
	v_cvt_pk_bf16_f32 v122, v140, v141
	v_cvt_pk_bf16_f32 v123, v142, v143
	global_store_dwordx4 v[130:131], v[120:123], off
	v_lshlrev_b32_e32 v124, 16, v150
	v_and_b32_e32 v125, 0xffff0000, v150
	v_lshlrev_b32_e32 v120, 16, v151
	v_and_b32_e32 v121, 0xffff0000, v151
	v_pk_mul_f32 v[118:119], v[118:119], v[120:121]
	v_lshlrev_b32_e32 v120, 16, v152
	v_and_b32_e32 v121, 0xffff0000, v152
	v_pk_mul_f32 v[120:121], v[112:113], v[120:121]
	v_lshlrev_b32_e32 v112, 16, v153
	v_and_b32_e32 v113, 0xffff0000, v153
	v_pk_mul_f32 v[116:117], v[116:117], v[124:125]
	v_pk_mul_f32 v[122:123], v[114:115], v[112:113]
	v_cvt_pk_bf16_f32 v112, v116, v117
	v_cvt_pk_bf16_f32 v113, v118, v119
	v_cvt_pk_bf16_f32 v114, v120, v121
	v_cvt_pk_bf16_f32 v115, v122, v123
	global_store_dwordx4 v[130:131], v[112:115], off offset:256
	s_nop 1
	v_or_b32_e32 v112, 16, v132
	v_ashrrev_i32_e32 v113, 31, v112
	v_lshlrev_b64 v[112:113], 11, v[112:113]
	v_lshl_add_u64 v[112:113], s[24:25], 0, v[112:113]
	v_lshl_add_u64 v[116:117], v[112:113], 0, v[134:135]
	v_lshlrev_b32_e32 v118, 16, v154
	v_and_b32_e32 v119, 0xffff0000, v154
	v_lshlrev_b32_e32 v112, 16, v155
	v_and_b32_e32 v113, 0xffff0000, v155
	v_pk_mul_f32 v[110:111], v[110:111], v[112:113]
	v_lshlrev_b32_e32 v112, 16, v156
	v_and_b32_e32 v113, 0xffff0000, v156
	v_pk_mul_f32 v[112:113], v[104:105], v[112:113]
	v_lshlrev_b32_e32 v104, 16, v157
	v_and_b32_e32 v105, 0xffff0000, v157
	v_pk_mul_f32 v[108:109], v[108:109], v[118:119]
	v_pk_mul_f32 v[114:115], v[106:107], v[104:105]
	v_cvt_pk_bf16_f32 v104, v108, v109
	v_cvt_pk_bf16_f32 v105, v110, v111
	v_cvt_pk_bf16_f32 v106, v112, v113
	v_cvt_pk_bf16_f32 v107, v114, v115
	global_store_dwordx4 v[116:117], v[104:107], off
	v_lshlrev_b32_e32 v108, 16, v158
	v_and_b32_e32 v109, 0xffff0000, v158
	v_lshlrev_b32_e32 v104, 16, v159
	v_and_b32_e32 v105, 0xffff0000, v159
	v_pk_mul_f32 v[102:103], v[102:103], v[104:105]
	v_lshlrev_b32_e32 v104, 16, v160
	v_and_b32_e32 v105, 0xffff0000, v160
	v_pk_mul_f32 v[104:105], v[96:97], v[104:105]
	v_lshlrev_b32_e32 v96, 16, v161
	v_and_b32_e32 v97, 0xffff0000, v161
	v_pk_mul_f32 v[100:101], v[100:101], v[108:109]
	v_pk_mul_f32 v[106:107], v[98:99], v[96:97]
	v_cvt_pk_bf16_f32 v96, v100, v101
	v_cvt_pk_bf16_f32 v97, v102, v103
	v_cvt_pk_bf16_f32 v98, v104, v105
	v_cvt_pk_bf16_f32 v99, v106, v107
	global_store_dwordx4 v[116:117], v[96:99], off offset:256
	s_nop 1
	v_or_b32_e32 v96, 32, v132
	v_ashrrev_i32_e32 v97, 31, v96
	v_lshlrev_b64 v[96:97], 11, v[96:97]
	v_lshl_add_u64 v[96:97], s[24:25], 0, v[96:97]
	v_lshl_add_u64 v[100:101], v[96:97], 0, v[134:135]
	v_lshlrev_b32_e32 v102, 16, v162
	v_and_b32_e32 v103, 0xffff0000, v162
	v_lshlrev_b32_e32 v96, 16, v163
	v_and_b32_e32 v97, 0xffff0000, v163
	v_pk_mul_f32 v[94:95], v[94:95], v[96:97]
	v_lshlrev_b32_e32 v96, 16, v164
	v_and_b32_e32 v97, 0xffff0000, v164
	v_pk_mul_f32 v[96:97], v[88:89], v[96:97]
	v_lshlrev_b32_e32 v88, 16, v165
	v_and_b32_e32 v89, 0xffff0000, v165
	v_pk_mul_f32 v[92:93], v[92:93], v[102:103]
	v_pk_mul_f32 v[98:99], v[90:91], v[88:89]
	v_cvt_pk_bf16_f32 v88, v92, v93
	v_cvt_pk_bf16_f32 v89, v94, v95
	v_cvt_pk_bf16_f32 v90, v96, v97
	v_cvt_pk_bf16_f32 v91, v98, v99
	global_store_dwordx4 v[100:101], v[88:91], off
	v_lshlrev_b32_e32 v92, 16, v182
	v_and_b32_e32 v93, 0xffff0000, v182
	v_lshlrev_b32_e32 v88, 16, v183
	v_and_b32_e32 v89, 0xffff0000, v183
	v_pk_mul_f32 v[86:87], v[86:87], v[88:89]
	v_lshlrev_b32_e32 v88, 16, v184
	v_and_b32_e32 v89, 0xffff0000, v184
	v_pk_mul_f32 v[88:89], v[80:81], v[88:89]
	v_lshlrev_b32_e32 v80, 16, v185
	v_and_b32_e32 v81, 0xffff0000, v185
	v_pk_mul_f32 v[84:85], v[84:85], v[92:93]
	v_pk_mul_f32 v[90:91], v[82:83], v[80:81]
	v_cvt_pk_bf16_f32 v80, v84, v85
	v_cvt_pk_bf16_f32 v81, v86, v87
	v_cvt_pk_bf16_f32 v82, v88, v89
	v_cvt_pk_bf16_f32 v83, v90, v91
	global_store_dwordx4 v[100:101], v[80:83], off offset:256
	s_nop 1
	v_or_b32_e32 v80, 48, v132
	v_ashrrev_i32_e32 v81, 31, v80
	v_lshlrev_b64 v[80:81], 11, v[80:81]
	v_lshl_add_u64 v[80:81], s[24:25], 0, v[80:81]
	v_lshl_add_u64 v[84:85], v[80:81], 0, v[134:135]
	v_lshlrev_b32_e32 v86, 16, v186
	v_and_b32_e32 v87, 0xffff0000, v186
	v_lshlrev_b32_e32 v80, 16, v187
	v_and_b32_e32 v81, 0xffff0000, v187
	v_pk_mul_f32 v[78:79], v[78:79], v[80:81]
	v_lshlrev_b32_e32 v80, 16, v188
	v_and_b32_e32 v81, 0xffff0000, v188
	v_pk_mul_f32 v[80:81], v[72:73], v[80:81]
	v_lshlrev_b32_e32 v72, 16, v189
	v_and_b32_e32 v73, 0xffff0000, v189
	v_pk_mul_f32 v[76:77], v[76:77], v[86:87]
	v_pk_mul_f32 v[82:83], v[74:75], v[72:73]
	v_cvt_pk_bf16_f32 v72, v76, v77
	v_cvt_pk_bf16_f32 v73, v78, v79
	v_cvt_pk_bf16_f32 v74, v80, v81
	v_cvt_pk_bf16_f32 v75, v82, v83
	global_store_dwordx4 v[84:85], v[72:75], off
	v_lshlrev_b32_e32 v76, 16, v190
	v_and_b32_e32 v77, 0xffff0000, v190
	v_lshlrev_b32_e32 v72, 16, v191
	v_and_b32_e32 v73, 0xffff0000, v191
	v_pk_mul_f32 v[70:71], v[70:71], v[72:73]
	v_lshlrev_b32_e32 v72, 16, v192
	v_and_b32_e32 v73, 0xffff0000, v192
	v_pk_mul_f32 v[72:73], v[64:65], v[72:73]
	v_lshlrev_b32_e32 v64, 16, v193
	v_and_b32_e32 v65, 0xffff0000, v193
	v_pk_mul_f32 v[68:69], v[68:69], v[76:77]
	v_pk_mul_f32 v[74:75], v[66:67], v[64:65]
	v_cvt_pk_bf16_f32 v65, v70, v71
	v_add_co_u32_e32 v70, vcc, s93, v130
	v_cvt_pk_bf16_f32 v64, v68, v69
	v_cvt_pk_bf16_f32 v66, v72, v73
	v_cvt_pk_bf16_f32 v67, v74, v75
	v_addc_co_u32_e32 v71, vcc, 0, v131, vcc
	global_store_dwordx4 v[84:85], v[64:67], off offset:256
	v_lshlrev_b32_e32 v72, 16, v194
	v_and_b32_e32 v73, 0xffff0000, v194
	v_lshlrev_b32_e32 v66, 16, v195
	v_and_b32_e32 v67, 0xffff0000, v195
	v_pk_mul_f32 v[62:63], v[62:63], v[66:67]
	v_lshlrev_b32_e32 v66, 16, v196
	v_and_b32_e32 v67, 0xffff0000, v196
	v_pk_mul_f32 v[66:67], v[56:57], v[66:67]
	v_lshlrev_b32_e32 v56, 16, v197
	v_and_b32_e32 v57, 0xffff0000, v197
	v_pk_mul_f32 v[60:61], v[60:61], v[72:73]
	v_pk_mul_f32 v[68:69], v[58:59], v[56:57]
	v_lshl_add_u64 v[64:65], v[130:131], 0, s[4:5]
	v_cvt_pk_bf16_f32 v56, v60, v61
	v_cvt_pk_bf16_f32 v57, v62, v63
	v_cvt_pk_bf16_f32 v58, v66, v67
	v_cvt_pk_bf16_f32 v59, v68, v69
	global_store_dwordx4 v[70:71], v[56:59], off
	v_lshlrev_b32_e32 v60, 16, v198
	v_and_b32_e32 v61, 0xffff0000, v198
	v_lshlrev_b32_e32 v56, 16, v199
	v_and_b32_e32 v57, 0xffff0000, v199
	v_pk_mul_f32 v[54:55], v[54:55], v[56:57]
	v_lshlrev_b32_e32 v56, 16, v200
	v_and_b32_e32 v57, 0xffff0000, v200
	v_pk_mul_f32 v[56:57], v[48:49], v[56:57]
	v_lshlrev_b32_e32 v48, 16, v201
	v_and_b32_e32 v49, 0xffff0000, v201
	v_pk_mul_f32 v[52:53], v[52:53], v[60:61]
	v_pk_mul_f32 v[58:59], v[50:51], v[48:49]
	v_cvt_pk_bf16_f32 v49, v54, v55
	v_add_co_u32_e32 v54, vcc, s96, v130
	v_cvt_pk_bf16_f32 v48, v52, v53
	v_cvt_pk_bf16_f32 v50, v56, v57
	v_cvt_pk_bf16_f32 v51, v58, v59
	v_addc_co_u32_e32 v55, vcc, 0, v131, vcc
	global_store_dwordx4 v[64:65], v[48:51], off offset:256
	v_lshlrev_b32_e32 v56, 16, v202
	v_and_b32_e32 v57, 0xffff0000, v202
	v_lshlrev_b32_e32 v50, 16, v203
	v_and_b32_e32 v51, 0xffff0000, v203
	v_pk_mul_f32 v[46:47], v[46:47], v[50:51]
	v_lshlrev_b32_e32 v50, 16, v204
	v_and_b32_e32 v51, 0xffff0000, v204
	v_pk_mul_f32 v[50:51], v[40:41], v[50:51]
	v_lshlrev_b32_e32 v40, 16, v205
	v_and_b32_e32 v41, 0xffff0000, v205
	v_pk_mul_f32 v[44:45], v[44:45], v[56:57]
	v_pk_mul_f32 v[52:53], v[42:43], v[40:41]
	v_lshl_add_u64 v[48:49], v[130:131], 0, s[2:3]
	v_cvt_pk_bf16_f32 v40, v44, v45
	v_cvt_pk_bf16_f32 v41, v46, v47
	v_cvt_pk_bf16_f32 v42, v50, v51
	v_cvt_pk_bf16_f32 v43, v52, v53
	global_store_dwordx4 v[54:55], v[40:43], off
	s_mov_b64 s[2:3], 0x50000
	v_lshlrev_b32_e32 v44, 16, v206
	v_and_b32_e32 v45, 0xffff0000, v206
	v_lshlrev_b32_e32 v40, 16, v207
	v_and_b32_e32 v41, 0xffff0000, v207
	v_pk_mul_f32 v[38:39], v[38:39], v[40:41]
	v_lshlrev_b32_e32 v40, 16, v208
	v_and_b32_e32 v41, 0xffff0000, v208
	v_pk_mul_f32 v[40:41], v[32:33], v[40:41]
	v_lshlrev_b32_e32 v32, 16, v209
	v_and_b32_e32 v33, 0xffff0000, v209
	v_pk_mul_f32 v[36:37], v[36:37], v[44:45]
	v_pk_mul_f32 v[42:43], v[34:35], v[32:33]
	v_cvt_pk_bf16_f32 v32, v36, v37
	v_cvt_pk_bf16_f32 v33, v38, v39
	v_cvt_pk_bf16_f32 v34, v40, v41
	v_cvt_pk_bf16_f32 v35, v42, v43
	global_store_dwordx4 v[48:49], v[32:35], off offset:256
	s_nop 1
	v_lshl_add_u64 v[32:33], v[130:131], 0, s[2:3]
	s_mov_b32 s2, 0x50000
	v_add_co_u32_e32 v38, vcc, s2, v130
	s_mov_b64 s[2:3], 0x58000
	s_nop 0
	v_addc_co_u32_e32 v39, vcc, 0, v131, vcc
	v_lshlrev_b32_e32 v40, 16, v220
	v_and_b32_e32 v41, 0xffff0000, v220
	v_lshlrev_b32_e32 v34, 16, v221
	v_and_b32_e32 v35, 0xffff0000, v221
	v_pk_mul_f32 v[30:31], v[30:31], v[34:35]
	v_lshlrev_b32_e32 v34, 16, v222
	v_and_b32_e32 v35, 0xffff0000, v222
	v_pk_mul_f32 v[34:35], v[24:25], v[34:35]
	v_lshlrev_b32_e32 v24, 16, v223
	v_and_b32_e32 v25, 0xffff0000, v223
	v_pk_mul_f32 v[28:29], v[28:29], v[40:41]
	v_pk_mul_f32 v[36:37], v[26:27], v[24:25]
	v_cvt_pk_bf16_f32 v24, v28, v29
	v_cvt_pk_bf16_f32 v25, v30, v31
	v_cvt_pk_bf16_f32 v26, v34, v35
	v_cvt_pk_bf16_f32 v27, v36, v37
	global_store_dwordx4 v[38:39], v[24:27], off
	v_lshlrev_b32_e32 v28, 16, v224
	v_and_b32_e32 v29, 0xffff0000, v224
	v_lshlrev_b32_e32 v24, 16, v225
	v_and_b32_e32 v25, 0xffff0000, v225
	v_pk_mul_f32 v[22:23], v[22:23], v[24:25]
	v_lshlrev_b32_e32 v24, 16, v226
	v_and_b32_e32 v25, 0xffff0000, v226
	v_pk_mul_f32 v[24:25], v[16:17], v[24:25]
	v_lshlrev_b32_e32 v16, 16, v227
	v_and_b32_e32 v17, 0xffff0000, v227
	v_pk_mul_f32 v[20:21], v[20:21], v[28:29]
	v_pk_mul_f32 v[26:27], v[18:19], v[16:17]
	v_cvt_pk_bf16_f32 v16, v20, v21
	v_cvt_pk_bf16_f32 v17, v22, v23
	v_cvt_pk_bf16_f32 v18, v24, v25
	v_cvt_pk_bf16_f32 v19, v26, v27
	global_store_dwordx4 v[32:33], v[16:19], off offset:256
	s_nop 1
	v_lshl_add_u64 v[16:17], v[130:131], 0, s[2:3]
	s_mov_b32 s2, 0x58000
	v_add_co_u32_e32 v22, vcc, s2, v130
	s_mov_b64 s[2:3], -1
	s_nop 0
	v_addc_co_u32_e32 v23, vcc, 0, v131, vcc
	s_andn2_b64 vcc, exec, s[36:37]
	v_lshlrev_b32_e32 v24, 16, v228
	v_and_b32_e32 v25, 0xffff0000, v228
	v_lshlrev_b32_e32 v18, 16, v229
	v_and_b32_e32 v19, 0xffff0000, v229
	v_pk_mul_f32 v[14:15], v[14:15], v[18:19]
	v_lshlrev_b32_e32 v18, 16, v230
	v_and_b32_e32 v19, 0xffff0000, v230
	v_pk_mul_f32 v[18:19], v[8:9], v[18:19]
	v_lshlrev_b32_e32 v8, 16, v231
	v_and_b32_e32 v9, 0xffff0000, v231
	v_pk_mul_f32 v[12:13], v[12:13], v[24:25]
	v_pk_mul_f32 v[20:21], v[10:11], v[8:9]
	v_cvt_pk_bf16_f32 v8, v12, v13
	v_cvt_pk_bf16_f32 v9, v14, v15
	v_cvt_pk_bf16_f32 v10, v18, v19
	v_cvt_pk_bf16_f32 v11, v20, v21
	global_store_dwordx4 v[22:23], v[8:11], off
	v_lshlrev_b32_e32 v12, 16, v232
	v_and_b32_e32 v13, 0xffff0000, v232
	v_lshlrev_b32_e32 v8, 16, v233
	v_and_b32_e32 v9, 0xffff0000, v233
	v_pk_mul_f32 v[6:7], v[6:7], v[8:9]
	v_lshlrev_b32_e32 v8, 16, v234
	v_and_b32_e32 v9, 0xffff0000, v234
	v_pk_mul_f32 v[8:9], v[0:1], v[8:9]
	v_lshlrev_b32_e32 v0, 16, v235
	v_and_b32_e32 v1, 0xffff0000, v235
	v_pk_mul_f32 v[4:5], v[4:5], v[12:13]
	v_pk_mul_f32 v[10:11], v[2:3], v[0:1]
	v_cvt_pk_bf16_f32 v0, v4, v5
	v_cvt_pk_bf16_f32 v1, v6, v7
	v_cvt_pk_bf16_f32 v2, v8, v9
	v_cvt_pk_bf16_f32 v3, v10, v11
	global_store_dwordx4 v[16:17], v[0:3], off offset:256
	s_cbranch_vccnz .LBB0_752
	s_andn2_b64 vcc, exec, s[0:1]
	s_cbranch_vccnz .LBB0_751
	s_barrier
	s_branch .LBB0_751

.LBB0_787:
	v_mov_b32_e32 v130, v136
	s_lshl_b32 s2, s2, 8
	s_add_i32 s2, s2, s78
	v_and_or_b32 v134, v130, 15, s2
	s_lshl_b32 s2, s3, 8
	v_lshrrev_b32_e32 v130, 1, v130
	v_and_or_b32 v130, v130, 24, s2
	v_or_b32_e32 v132, s79, v130
	v_ashrrev_i32_e32 v135, 31, v134
	v_ashrrev_i32_e32 v133, 31, v132
	v_lshlrev_b64 v[130:131], 10, v[134:135]
	v_lshl_add_u64 v[130:131], v[130:131], 0, v[132:133]
	v_lshlrev_b64 v[130:131], 1, v[130:131]
	v_lshl_add_u64 v[148:149], s[24:25], 0, v[130:131]
	v_lshl_add_u64 v[150:151], s[28:29], 0, v[130:131]
	v_lshl_add_u64 v[246:247], s[24:25], 0, v[130:131]
	v_lshl_add_u64 v[248:249], s[28:29], 0, v[130:131]
	global_load_dwordx4 v[156:159], v[246:247], off
	global_load_dwordx4 v[160:163], v[248:249], off
	global_load_dwordx4 v[164:167], v[246:247], off offset:256
	global_load_dwordx4 v[182:185], v[248:249], off offset:256
	s_mov_b64 s[98:99], 0x8000
	v_lshl_add_u64 v[244:245], v[130:131], 0, s[98:99]
	v_lshl_add_u64 v[246:247], s[24:25], 0, v[244:245]
	v_lshl_add_u64 v[248:249], s[28:29], 0, v[244:245]
	global_load_dwordx4 v[186:189], v[246:247], off
	global_load_dwordx4 v[190:193], v[248:249], off
	global_load_dwordx4 v[194:197], v[246:247], off offset:256
	global_load_dwordx4 v[198:201], v[248:249], off offset:256
	s_mov_b64 s[98:99], 0x10000
	v_lshl_add_u64 v[244:245], v[130:131], 0, s[98:99]
	v_lshl_add_u64 v[246:247], s[24:25], 0, v[244:245]
	v_lshl_add_u64 v[248:249], s[28:29], 0, v[244:245]
	global_load_dwordx4 v[202:205], v[246:247], off
	global_load_dwordx4 v[206:209], v[248:249], off
	global_load_dwordx4 v[220:223], v[246:247], off offset:256
	global_load_dwordx4 v[224:227], v[248:249], off offset:256
	s_mov_b64 s[98:99], 0x18000
	v_lshl_add_u64 v[244:245], v[130:131], 0, s[98:99]
	v_lshl_add_u64 v[246:247], s[24:25], 0, v[244:245]
	v_lshl_add_u64 v[248:249], s[28:29], 0, v[244:245]
	global_load_dwordx4 v[228:231], v[246:247], off
	global_load_dwordx4 v[232:235], v[248:249], off
	global_load_dwordx4 v[236:239], v[246:247], off offset:256
	global_load_dwordx4 v[240:243], v[248:249], off offset:256
	s_waitcnt vmcnt(0)
	s_mov_b64 s[2:3], 0x48000
	s_andn2_b64 vcc, exec, s[36:37]
	v_lshlrev_b32_e32 v152, 16, v156
	v_and_b32_e32 v153, 0xffff0000, v156
	v_lshlrev_b32_e32 v154, 16, v160
	v_and_b32_e32 v155, 0xffff0000, v160
	v_lshlrev_b32_e32 v140, 16, v157
	v_and_b32_e32 v141, 0xffff0000, v157
	v_lshlrev_b32_e32 v144, 16, v161
	v_and_b32_e32 v145, 0xffff0000, v161
	v_pk_fma_f32 v[126:127], v[126:127], v[144:145], v[140:141]
	v_lshlrev_b32_e32 v140, 16, v158
	v_and_b32_e32 v141, 0xffff0000, v158
	v_lshlrev_b32_e32 v144, 16, v162
	v_and_b32_e32 v145, 0xffff0000, v162
	v_pk_fma_f32 v[140:141], v[120:121], v[144:145], v[140:141]
	v_lshlrev_b32_e32 v120, 16, v159
	v_and_b32_e32 v121, 0xffff0000, v159
	v_lshlrev_b32_e32 v142, 16, v163
	v_and_b32_e32 v143, 0xffff0000, v163
	v_pk_fma_f32 v[124:125], v[124:125], v[154:155], v[152:153]
	v_pk_fma_f32 v[142:143], v[122:123], v[142:143], v[120:121]
	v_cvt_pk_bf16_f32 v120, v124, v125
	v_cvt_pk_bf16_f32 v121, v126, v127
	v_cvt_pk_bf16_f32 v122, v140, v141
	v_cvt_pk_bf16_f32 v123, v142, v143
	global_store_dwordx4 v[148:149], v[120:123], off
	s_nop 0
	v_lshlrev_b32_e32 v140, 16, v164
	v_and_b32_e32 v141, 0xffff0000, v164
	v_lshlrev_b32_e32 v142, 16, v182
	v_and_b32_e32 v143, 0xffff0000, v182
	v_lshlrev_b32_e32 v120, 16, v165
	v_and_b32_e32 v121, 0xffff0000, v165
	v_lshlrev_b32_e32 v124, 16, v183
	v_and_b32_e32 v125, 0xffff0000, v183
	v_pk_fma_f32 v[118:119], v[118:119], v[124:125], v[120:121]
	v_lshlrev_b32_e32 v120, 16, v166
	v_and_b32_e32 v121, 0xffff0000, v166
	v_lshlrev_b32_e32 v124, 16, v184
	v_and_b32_e32 v125, 0xffff0000, v184
	v_pk_fma_f32 v[120:121], v[112:113], v[124:125], v[120:121]
	v_lshlrev_b32_e32 v112, 16, v167
	v_and_b32_e32 v113, 0xffff0000, v167
	v_lshlrev_b32_e32 v122, 16, v185
	v_and_b32_e32 v123, 0xffff0000, v185
	v_pk_fma_f32 v[116:117], v[116:117], v[142:143], v[140:141]
	v_pk_fma_f32 v[122:123], v[114:115], v[122:123], v[112:113]
	v_cvt_pk_bf16_f32 v112, v116, v117
	v_cvt_pk_bf16_f32 v113, v118, v119
	v_cvt_pk_bf16_f32 v114, v120, v121
	v_cvt_pk_bf16_f32 v115, v122, v123
	global_store_dwordx4 v[148:149], v[112:115], off offset:256
	s_nop 1
	v_or_b32_e32 v112, 16, v134
	v_ashrrev_i32_e32 v113, 31, v112
	v_lshlrev_b64 v[112:113], 10, v[112:113]
	v_lshl_add_u64 v[112:113], v[112:113], 0, v[132:133]
	v_lshlrev_b64 v[118:119], 1, v[112:113]
	v_lshl_add_u64 v[112:113], s[24:25], 0, v[118:119]
	v_lshl_add_u64 v[122:123], s[28:29], 0, v[118:119]
	v_lshlrev_b32_e32 v124, 16, v186
	v_and_b32_e32 v125, 0xffff0000, v186
	v_lshlrev_b32_e32 v126, 16, v190
	v_and_b32_e32 v127, 0xffff0000, v190
	v_lshlrev_b32_e32 v114, 16, v187
	v_and_b32_e32 v115, 0xffff0000, v187
	v_lshlrev_b32_e32 v118, 16, v191
	v_and_b32_e32 v119, 0xffff0000, v191
	v_pk_fma_f32 v[110:111], v[110:111], v[118:119], v[114:115]
	v_lshlrev_b32_e32 v114, 16, v188
	v_and_b32_e32 v115, 0xffff0000, v188
	v_lshlrev_b32_e32 v118, 16, v192
	v_and_b32_e32 v119, 0xffff0000, v192
	v_pk_fma_f32 v[114:115], v[104:105], v[118:119], v[114:115]
	v_lshlrev_b32_e32 v104, 16, v189
	v_and_b32_e32 v105, 0xffff0000, v189
	v_lshlrev_b32_e32 v116, 16, v193
	v_and_b32_e32 v117, 0xffff0000, v193
	v_pk_fma_f32 v[108:109], v[108:109], v[126:127], v[124:125]
	v_pk_fma_f32 v[116:117], v[106:107], v[116:117], v[104:105]
	v_cvt_pk_bf16_f32 v104, v108, v109
	v_cvt_pk_bf16_f32 v105, v110, v111
	v_cvt_pk_bf16_f32 v106, v114, v115
	v_cvt_pk_bf16_f32 v107, v116, v117
	global_store_dwordx4 v[112:113], v[104:107], off
	s_nop 0
	v_lshlrev_b32_e32 v114, 16, v194
	v_and_b32_e32 v115, 0xffff0000, v194
	v_lshlrev_b32_e32 v116, 16, v198
	v_and_b32_e32 v117, 0xffff0000, v198
	v_lshlrev_b32_e32 v104, 16, v195
	v_and_b32_e32 v105, 0xffff0000, v195
	v_lshlrev_b32_e32 v108, 16, v199
	v_and_b32_e32 v109, 0xffff0000, v199
	v_pk_fma_f32 v[102:103], v[102:103], v[108:109], v[104:105]
	v_lshlrev_b32_e32 v104, 16, v196
	v_and_b32_e32 v105, 0xffff0000, v196
	v_lshlrev_b32_e32 v108, 16, v200
	v_and_b32_e32 v109, 0xffff0000, v200
	v_pk_fma_f32 v[104:105], v[96:97], v[108:109], v[104:105]
	v_lshlrev_b32_e32 v96, 16, v197
	v_and_b32_e32 v97, 0xffff0000, v197
	v_lshlrev_b32_e32 v106, 16, v201
	v_and_b32_e32 v107, 0xffff0000, v201
	v_pk_fma_f32 v[100:101], v[100:101], v[116:117], v[114:115]
	v_pk_fma_f32 v[106:107], v[98:99], v[106:107], v[96:97]
	v_cvt_pk_bf16_f32 v96, v100, v101
	v_cvt_pk_bf16_f32 v97, v102, v103
	v_cvt_pk_bf16_f32 v98, v104, v105
	v_cvt_pk_bf16_f32 v99, v106, v107
	global_store_dwordx4 v[112:113], v[96:99], off offset:256
	s_nop 1
	v_or_b32_e32 v96, 32, v134
	v_ashrrev_i32_e32 v97, 31, v96
	v_lshlrev_b64 v[96:97], 10, v[96:97]
	v_lshl_add_u64 v[96:97], v[96:97], 0, v[132:133]
	v_lshlrev_b64 v[102:103], 1, v[96:97]
	v_lshl_add_u64 v[96:97], s[24:25], 0, v[102:103]
	v_lshl_add_u64 v[106:107], s[28:29], 0, v[102:103]
	v_lshlrev_b32_e32 v108, 16, v202
	v_and_b32_e32 v109, 0xffff0000, v202
	v_lshlrev_b32_e32 v110, 16, v206
	v_and_b32_e32 v111, 0xffff0000, v206
	v_lshlrev_b32_e32 v98, 16, v203
	v_and_b32_e32 v99, 0xffff0000, v203
	v_lshlrev_b32_e32 v102, 16, v207
	v_and_b32_e32 v103, 0xffff0000, v207
	v_pk_fma_f32 v[94:95], v[94:95], v[102:103], v[98:99]
	v_lshlrev_b32_e32 v98, 16, v204
	v_and_b32_e32 v99, 0xffff0000, v204
	v_lshlrev_b32_e32 v102, 16, v208
	v_and_b32_e32 v103, 0xffff0000, v208
	v_pk_fma_f32 v[98:99], v[88:89], v[102:103], v[98:99]
	v_lshlrev_b32_e32 v88, 16, v205
	v_and_b32_e32 v89, 0xffff0000, v205
	v_lshlrev_b32_e32 v100, 16, v209
	v_and_b32_e32 v101, 0xffff0000, v209
	v_pk_fma_f32 v[92:93], v[92:93], v[110:111], v[108:109]
	v_pk_fma_f32 v[100:101], v[90:91], v[100:101], v[88:89]
	v_cvt_pk_bf16_f32 v88, v92, v93
	v_cvt_pk_bf16_f32 v89, v94, v95
	v_cvt_pk_bf16_f32 v90, v98, v99
	v_cvt_pk_bf16_f32 v91, v100, v101
	global_store_dwordx4 v[96:97], v[88:91], off
	s_nop 0
	v_lshlrev_b32_e32 v98, 16, v220
	v_and_b32_e32 v99, 0xffff0000, v220
	v_lshlrev_b32_e32 v100, 16, v224
	v_and_b32_e32 v101, 0xffff0000, v224
	v_lshlrev_b32_e32 v88, 16, v221
	v_and_b32_e32 v89, 0xffff0000, v221
	v_lshlrev_b32_e32 v92, 16, v225
	v_and_b32_e32 v93, 0xffff0000, v225
	v_pk_fma_f32 v[86:87], v[86:87], v[92:93], v[88:89]
	v_lshlrev_b32_e32 v88, 16, v222
	v_and_b32_e32 v89, 0xffff0000, v222
	v_lshlrev_b32_e32 v92, 16, v226
	v_and_b32_e32 v93, 0xffff0000, v226
	v_pk_fma_f32 v[88:89], v[80:81], v[92:93], v[88:89]
	v_lshlrev_b32_e32 v80, 16, v223
	v_and_b32_e32 v81, 0xffff0000, v223
	v_lshlrev_b32_e32 v90, 16, v227
	v_and_b32_e32 v91, 0xffff0000, v227
	v_pk_fma_f32 v[84:85], v[84:85], v[100:101], v[98:99]
	v_pk_fma_f32 v[90:91], v[82:83], v[90:91], v[80:81]
	v_cvt_pk_bf16_f32 v80, v84, v85
	v_cvt_pk_bf16_f32 v81, v86, v87
	v_cvt_pk_bf16_f32 v82, v88, v89
	v_cvt_pk_bf16_f32 v83, v90, v91
	global_store_dwordx4 v[96:97], v[80:83], off offset:256
	s_nop 1
	v_or_b32_e32 v80, 48, v134
	v_ashrrev_i32_e32 v81, 31, v80
	v_lshlrev_b64 v[80:81], 10, v[80:81]
	v_lshl_add_u64 v[80:81], v[80:81], 0, v[132:133]
	v_lshlrev_b64 v[86:87], 1, v[80:81]
	v_lshl_add_u64 v[80:81], s[24:25], 0, v[86:87]
	v_lshl_add_u64 v[90:91], s[28:29], 0, v[86:87]
	v_lshlrev_b32_e32 v92, 16, v228
	v_and_b32_e32 v93, 0xffff0000, v228
	v_lshlrev_b32_e32 v94, 16, v232
	v_and_b32_e32 v95, 0xffff0000, v232
	v_lshlrev_b32_e32 v82, 16, v229
	v_and_b32_e32 v83, 0xffff0000, v229
	v_lshlrev_b32_e32 v86, 16, v233
	v_and_b32_e32 v87, 0xffff0000, v233
	v_pk_fma_f32 v[78:79], v[78:79], v[86:87], v[82:83]
	v_lshlrev_b32_e32 v82, 16, v230
	v_and_b32_e32 v83, 0xffff0000, v230
	v_lshlrev_b32_e32 v86, 16, v234
	v_and_b32_e32 v87, 0xffff0000, v234
	v_pk_fma_f32 v[82:83], v[72:73], v[86:87], v[82:83]
	v_lshlrev_b32_e32 v72, 16, v231
	v_and_b32_e32 v73, 0xffff0000, v231
	v_lshlrev_b32_e32 v84, 16, v235
	v_and_b32_e32 v85, 0xffff0000, v235
	v_pk_fma_f32 v[76:77], v[76:77], v[94:95], v[92:93]
	v_pk_fma_f32 v[84:85], v[74:75], v[84:85], v[72:73]
	v_cvt_pk_bf16_f32 v72, v76, v77
	v_cvt_pk_bf16_f32 v73, v78, v79
	v_cvt_pk_bf16_f32 v74, v82, v83
	v_cvt_pk_bf16_f32 v75, v84, v85
	global_store_dwordx4 v[80:81], v[72:75], off
	s_nop 0
	v_lshlrev_b32_e32 v82, 16, v236
	v_and_b32_e32 v83, 0xffff0000, v236
	v_lshlrev_b32_e32 v84, 16, v240
	v_and_b32_e32 v85, 0xffff0000, v240
	v_lshlrev_b32_e32 v72, 16, v237
	v_and_b32_e32 v73, 0xffff0000, v237
	v_lshlrev_b32_e32 v76, 16, v241
	v_and_b32_e32 v77, 0xffff0000, v241
	v_pk_fma_f32 v[70:71], v[70:71], v[76:77], v[72:73]
	v_lshlrev_b32_e32 v72, 16, v238
	v_and_b32_e32 v73, 0xffff0000, v238
	v_lshlrev_b32_e32 v76, 16, v242
	v_and_b32_e32 v77, 0xffff0000, v242
	v_pk_fma_f32 v[72:73], v[64:65], v[76:77], v[72:73]
	v_lshlrev_b32_e32 v64, 16, v239
	v_and_b32_e32 v65, 0xffff0000, v239
	v_lshlrev_b32_e32 v74, 16, v243
	v_and_b32_e32 v75, 0xffff0000, v243
	v_pk_fma_f32 v[68:69], v[68:69], v[84:85], v[82:83]
	v_pk_fma_f32 v[74:75], v[66:67], v[74:75], v[64:65]
	v_cvt_pk_bf16_f32 v64, v68, v69
	v_cvt_pk_bf16_f32 v65, v70, v71
	v_cvt_pk_bf16_f32 v66, v72, v73
	v_cvt_pk_bf16_f32 v67, v74, v75
	v_lshl_add_u64 v[70:71], v[130:131], 0, s[4:5]
	global_store_dwordx4 v[80:81], v[64:67], off offset:256
	v_lshl_add_u64 v[74:75], s[28:29], 0, v[70:71]
	s_nop 0
	v_lshl_add_u64 v[64:65], s[24:25], 0, v[70:71]
	s_mov_b64 s[98:99], 0x40000
	v_lshl_add_u64 v[244:245], v[130:131], 0, s[98:99]
	v_lshl_add_u64 v[246:247], s[24:25], 0, v[244:245]
	v_lshl_add_u64 v[248:249], s[28:29], 0, v[244:245]
	global_load_dwordx4 v[156:159], v[246:247], off
	global_load_dwordx4 v[160:163], v[248:249], off
	global_load_dwordx4 v[164:167], v[246:247], off offset:256
	global_load_dwordx4 v[182:185], v[248:249], off offset:256
	s_mov_b64 s[98:99], 0x48000
	v_lshl_add_u64 v[244:245], v[130:131], 0, s[98:99]
	v_lshl_add_u64 v[246:247], s[24:25], 0, v[244:245]
	v_lshl_add_u64 v[248:249], s[28:29], 0, v[244:245]
	global_load_dwordx4 v[186:189], v[246:247], off
	global_load_dwordx4 v[190:193], v[248:249], off
	global_load_dwordx4 v[194:197], v[246:247], off offset:256
	global_load_dwordx4 v[198:201], v[248:249], off offset:256
	s_mov_b64 s[98:99], 0x50000
	v_lshl_add_u64 v[244:245], v[130:131], 0, s[98:99]
	v_lshl_add_u64 v[246:247], s[24:25], 0, v[244:245]
	v_lshl_add_u64 v[248:249], s[28:29], 0, v[244:245]
	global_load_dwordx4 v[202:205], v[246:247], off
	global_load_dwordx4 v[206:209], v[248:249], off
	global_load_dwordx4 v[220:223], v[246:247], off offset:256
	global_load_dwordx4 v[224:227], v[248:249], off offset:256
	s_mov_b64 s[98:99], 0x58000
	v_lshl_add_u64 v[244:245], v[130:131], 0, s[98:99]
	v_lshl_add_u64 v[246:247], s[24:25], 0, v[244:245]
	v_lshl_add_u64 v[248:249], s[28:29], 0, v[244:245]
	global_load_dwordx4 v[228:231], v[246:247], off
	global_load_dwordx4 v[232:235], v[248:249], off
	global_load_dwordx4 v[236:239], v[246:247], off offset:256
	global_load_dwordx4 v[240:243], v[248:249], off offset:256
	s_waitcnt vmcnt(0)
	v_lshlrev_b32_e32 v76, 16, v156
	v_and_b32_e32 v77, 0xffff0000, v156
	v_lshlrev_b32_e32 v78, 16, v160
	v_and_b32_e32 v79, 0xffff0000, v160
	v_lshlrev_b32_e32 v66, 16, v157
	v_and_b32_e32 v67, 0xffff0000, v157
	v_lshlrev_b32_e32 v70, 16, v161
	v_and_b32_e32 v71, 0xffff0000, v161
	v_pk_fma_f32 v[62:63], v[62:63], v[70:71], v[66:67]
	v_lshlrev_b32_e32 v66, 16, v158
	v_and_b32_e32 v67, 0xffff0000, v158
	v_lshlrev_b32_e32 v70, 16, v162
	v_and_b32_e32 v71, 0xffff0000, v162
	v_pk_fma_f32 v[66:67], v[56:57], v[70:71], v[66:67]
	v_lshlrev_b32_e32 v56, 16, v159
	v_and_b32_e32 v57, 0xffff0000, v159
	v_lshlrev_b32_e32 v68, 16, v163
	v_and_b32_e32 v69, 0xffff0000, v163
	v_pk_fma_f32 v[60:61], v[60:61], v[78:79], v[76:77]
	v_pk_fma_f32 v[68:69], v[58:59], v[68:69], v[56:57]
	v_cvt_pk_bf16_f32 v56, v60, v61
	v_cvt_pk_bf16_f32 v57, v62, v63
	v_cvt_pk_bf16_f32 v58, v66, v67
	v_cvt_pk_bf16_f32 v59, v68, v69
	global_store_dwordx4 v[64:65], v[56:59], off
	s_nop 0
	v_lshlrev_b32_e32 v66, 16, v164
	v_and_b32_e32 v67, 0xffff0000, v164
	v_lshlrev_b32_e32 v68, 16, v182
	v_and_b32_e32 v69, 0xffff0000, v182
	v_lshlrev_b32_e32 v56, 16, v165
	v_and_b32_e32 v57, 0xffff0000, v165
	v_lshlrev_b32_e32 v60, 16, v183
	v_and_b32_e32 v61, 0xffff0000, v183
	v_pk_fma_f32 v[54:55], v[54:55], v[60:61], v[56:57]
	v_lshlrev_b32_e32 v56, 16, v166
	v_and_b32_e32 v57, 0xffff0000, v166
	v_lshlrev_b32_e32 v60, 16, v184
	v_and_b32_e32 v61, 0xffff0000, v184
	v_pk_fma_f32 v[56:57], v[48:49], v[60:61], v[56:57]
	v_lshlrev_b32_e32 v48, 16, v167
	v_and_b32_e32 v49, 0xffff0000, v167
	v_lshlrev_b32_e32 v58, 16, v185
	v_and_b32_e32 v59, 0xffff0000, v185
	v_pk_fma_f32 v[52:53], v[52:53], v[68:69], v[66:67]
	v_pk_fma_f32 v[58:59], v[50:51], v[58:59], v[48:49]
	v_cvt_pk_bf16_f32 v48, v52, v53
	v_cvt_pk_bf16_f32 v49, v54, v55
	v_cvt_pk_bf16_f32 v50, v56, v57
	v_cvt_pk_bf16_f32 v51, v58, v59
	v_lshl_add_u64 v[54:55], v[130:131], 0, s[2:3]
	global_store_dwordx4 v[64:65], v[48:51], off offset:256
	v_lshl_add_u64 v[58:59], s[28:29], 0, v[54:55]
	s_mov_b64 s[2:3], 0x50000
	v_lshl_add_u64 v[48:49], s[24:25], 0, v[54:55]
	v_lshlrev_b32_e32 v60, 16, v186
	v_and_b32_e32 v61, 0xffff0000, v186
	v_lshlrev_b32_e32 v62, 16, v190
	v_and_b32_e32 v63, 0xffff0000, v190
	v_lshlrev_b32_e32 v50, 16, v187
	v_and_b32_e32 v51, 0xffff0000, v187
	v_lshlrev_b32_e32 v54, 16, v191
	v_and_b32_e32 v55, 0xffff0000, v191
	v_pk_fma_f32 v[46:47], v[46:47], v[54:55], v[50:51]
	v_lshlrev_b32_e32 v50, 16, v188
	v_and_b32_e32 v51, 0xffff0000, v188
	v_lshlrev_b32_e32 v54, 16, v192
	v_and_b32_e32 v55, 0xffff0000, v192
	v_pk_fma_f32 v[50:51], v[40:41], v[54:55], v[50:51]
	v_lshlrev_b32_e32 v40, 16, v189
	v_and_b32_e32 v41, 0xffff0000, v189
	v_lshlrev_b32_e32 v52, 16, v193
	v_and_b32_e32 v53, 0xffff0000, v193
	v_pk_fma_f32 v[44:45], v[44:45], v[62:63], v[60:61]
	v_pk_fma_f32 v[52:53], v[42:43], v[52:53], v[40:41]
	v_cvt_pk_bf16_f32 v40, v44, v45
	v_cvt_pk_bf16_f32 v41, v46, v47
	v_cvt_pk_bf16_f32 v42, v50, v51
	v_cvt_pk_bf16_f32 v43, v52, v53
	global_store_dwordx4 v[48:49], v[40:43], off
	s_nop 0
	v_lshlrev_b32_e32 v50, 16, v194
	v_and_b32_e32 v51, 0xffff0000, v194
	v_lshlrev_b32_e32 v52, 16, v198
	v_and_b32_e32 v53, 0xffff0000, v198
	v_lshlrev_b32_e32 v40, 16, v195
	v_and_b32_e32 v41, 0xffff0000, v195
	v_lshlrev_b32_e32 v44, 16, v199
	v_and_b32_e32 v45, 0xffff0000, v199
	v_pk_fma_f32 v[38:39], v[38:39], v[44:45], v[40:41]
	v_lshlrev_b32_e32 v40, 16, v196
	v_and_b32_e32 v41, 0xffff0000, v196
	v_lshlrev_b32_e32 v44, 16, v200
	v_and_b32_e32 v45, 0xffff0000, v200
	v_pk_fma_f32 v[40:41], v[32:33], v[44:45], v[40:41]
	v_lshlrev_b32_e32 v32, 16, v197
	v_and_b32_e32 v33, 0xffff0000, v197
	v_lshlrev_b32_e32 v42, 16, v201
	v_and_b32_e32 v43, 0xffff0000, v201
	v_pk_fma_f32 v[36:37], v[36:37], v[52:53], v[50:51]
	v_pk_fma_f32 v[42:43], v[34:35], v[42:43], v[32:33]
	v_cvt_pk_bf16_f32 v32, v36, v37
	v_cvt_pk_bf16_f32 v33, v38, v39
	v_cvt_pk_bf16_f32 v34, v40, v41
	v_cvt_pk_bf16_f32 v35, v42, v43
	v_lshl_add_u64 v[38:39], v[130:131], 0, s[2:3]
	global_store_dwordx4 v[48:49], v[32:35], off offset:256
	v_lshl_add_u64 v[42:43], s[28:29], 0, v[38:39]
	s_mov_b64 s[2:3], 0x58000
	v_lshl_add_u64 v[32:33], s[24:25], 0, v[38:39]
	v_lshlrev_b32_e32 v44, 16, v202
	v_and_b32_e32 v45, 0xffff0000, v202
	v_lshlrev_b32_e32 v46, 16, v206
	v_and_b32_e32 v47, 0xffff0000, v206
	v_lshlrev_b32_e32 v34, 16, v203
	v_and_b32_e32 v35, 0xffff0000, v203
	v_lshlrev_b32_e32 v38, 16, v207
	v_and_b32_e32 v39, 0xffff0000, v207
	v_pk_fma_f32 v[30:31], v[30:31], v[38:39], v[34:35]
	v_lshlrev_b32_e32 v34, 16, v204
	v_and_b32_e32 v35, 0xffff0000, v204
	v_lshlrev_b32_e32 v38, 16, v208
	v_and_b32_e32 v39, 0xffff0000, v208
	v_pk_fma_f32 v[34:35], v[24:25], v[38:39], v[34:35]
	v_lshlrev_b32_e32 v24, 16, v205
	v_and_b32_e32 v25, 0xffff0000, v205
	v_lshlrev_b32_e32 v36, 16, v209
	v_and_b32_e32 v37, 0xffff0000, v209
	v_pk_fma_f32 v[28:29], v[28:29], v[46:47], v[44:45]
	v_pk_fma_f32 v[36:37], v[26:27], v[36:37], v[24:25]
	v_cvt_pk_bf16_f32 v24, v28, v29
	v_cvt_pk_bf16_f32 v25, v30, v31
	v_cvt_pk_bf16_f32 v26, v34, v35
	v_cvt_pk_bf16_f32 v27, v36, v37
	global_store_dwordx4 v[32:33], v[24:27], off
	s_nop 0
	v_lshlrev_b32_e32 v34, 16, v220
	v_and_b32_e32 v35, 0xffff0000, v220
	v_lshlrev_b32_e32 v36, 16, v224
	v_and_b32_e32 v37, 0xffff0000, v224
	v_lshlrev_b32_e32 v24, 16, v221
	v_and_b32_e32 v25, 0xffff0000, v221
	v_lshlrev_b32_e32 v28, 16, v225
	v_and_b32_e32 v29, 0xffff0000, v225
	v_pk_fma_f32 v[22:23], v[22:23], v[28:29], v[24:25]
	v_lshlrev_b32_e32 v24, 16, v222
	v_and_b32_e32 v25, 0xffff0000, v222
	v_lshlrev_b32_e32 v28, 16, v226
	v_and_b32_e32 v29, 0xffff0000, v226
	v_pk_fma_f32 v[24:25], v[16:17], v[28:29], v[24:25]
	v_lshlrev_b32_e32 v16, 16, v223
	v_and_b32_e32 v17, 0xffff0000, v223
	v_lshlrev_b32_e32 v26, 16, v227
	v_and_b32_e32 v27, 0xffff0000, v227
	v_pk_fma_f32 v[20:21], v[20:21], v[36:37], v[34:35]
	v_pk_fma_f32 v[26:27], v[18:19], v[26:27], v[16:17]
	v_cvt_pk_bf16_f32 v16, v20, v21
	v_cvt_pk_bf16_f32 v17, v22, v23
	v_cvt_pk_bf16_f32 v18, v24, v25
	v_cvt_pk_bf16_f32 v19, v26, v27
	v_lshl_add_u64 v[22:23], v[130:131], 0, s[2:3]
	global_store_dwordx4 v[32:33], v[16:19], off offset:256
	v_lshl_add_u64 v[26:27], s[28:29], 0, v[22:23]
	s_mov_b64 s[2:3], -1
	v_lshl_add_u64 v[16:17], s[24:25], 0, v[22:23]
	v_lshlrev_b32_e32 v28, 16, v228
	v_and_b32_e32 v29, 0xffff0000, v228
	v_lshlrev_b32_e32 v30, 16, v232
	v_and_b32_e32 v31, 0xffff0000, v232
	v_lshlrev_b32_e32 v18, 16, v229
	v_and_b32_e32 v19, 0xffff0000, v229
	v_lshlrev_b32_e32 v22, 16, v233
	v_and_b32_e32 v23, 0xffff0000, v233
	v_pk_fma_f32 v[14:15], v[14:15], v[22:23], v[18:19]
	v_lshlrev_b32_e32 v18, 16, v230
	v_and_b32_e32 v19, 0xffff0000, v230
	v_lshlrev_b32_e32 v22, 16, v234
	v_and_b32_e32 v23, 0xffff0000, v234
	v_pk_fma_f32 v[18:19], v[8:9], v[22:23], v[18:19]
	v_lshlrev_b32_e32 v8, 16, v231
	v_and_b32_e32 v9, 0xffff0000, v231
	v_lshlrev_b32_e32 v20, 16, v235
	v_and_b32_e32 v21, 0xffff0000, v235
	v_pk_fma_f32 v[12:13], v[12:13], v[30:31], v[28:29]
	v_pk_fma_f32 v[20:21], v[10:11], v[20:21], v[8:9]
	v_cvt_pk_bf16_f32 v8, v12, v13
	v_cvt_pk_bf16_f32 v9, v14, v15
	v_cvt_pk_bf16_f32 v10, v18, v19
	v_cvt_pk_bf16_f32 v11, v20, v21
	global_store_dwordx4 v[16:17], v[8:11], off
	s_nop 0
	v_lshlrev_b32_e32 v18, 16, v236
	v_and_b32_e32 v19, 0xffff0000, v236
	v_lshlrev_b32_e32 v20, 16, v240
	v_and_b32_e32 v21, 0xffff0000, v240
	v_lshlrev_b32_e32 v8, 16, v237
	v_and_b32_e32 v9, 0xffff0000, v237
	v_lshlrev_b32_e32 v12, 16, v241
	v_and_b32_e32 v13, 0xffff0000, v241
	v_pk_fma_f32 v[6:7], v[6:7], v[12:13], v[8:9]
	v_lshlrev_b32_e32 v8, 16, v238
	v_and_b32_e32 v9, 0xffff0000, v238
	v_lshlrev_b32_e32 v12, 16, v242
	v_and_b32_e32 v13, 0xffff0000, v242
	v_pk_fma_f32 v[8:9], v[0:1], v[12:13], v[8:9]
	v_lshlrev_b32_e32 v0, 16, v239
	v_and_b32_e32 v1, 0xffff0000, v239
	v_lshlrev_b32_e32 v10, 16, v243
	v_and_b32_e32 v11, 0xffff0000, v243
	v_pk_fma_f32 v[4:5], v[4:5], v[20:21], v[18:19]
	v_pk_fma_f32 v[10:11], v[2:3], v[10:11], v[0:1]
	v_cvt_pk_bf16_f32 v0, v4, v5
	v_cvt_pk_bf16_f32 v1, v6, v7
	v_cvt_pk_bf16_f32 v2, v8, v9
	v_cvt_pk_bf16_f32 v3, v10, v11
	global_store_dwordx4 v[16:17], v[0:3], off offset:256
	s_cbranch_vccnz .LBB0_776
	s_andn2_b64 vcc, exec, s[0:1]
	s_cbranch_vccnz .LBB0_775
	s_barrier
	s_branch .LBB0_775
